# baseline (speedup 1.0000x reference)
; template <int MODE> ...
;     ...
;   const int nM = M / BM, nN = N / BM, nwg = nM * nN;
;   const int tid = threadIdx.x;
;   const int wid = tid >> 6, lane = tid & 63, wr = wid >> 2, wc = wid & 3, fr = lane & 15, fq = lane >> 4;
;   const int tb16 = tid * 16;
;   int voff0, voff1;
;   { int R, C; stage_rc(tb16, R, C); voff0 = R * K + C; voff1 = voff0 + 64 * K; }
;   int sw = fr * 64 + fq * 16; sw ^= ((sw >> 9) & 1) << 5;
;   int aB = wr * 8192 + sw;
;   int bB = 65536 + wc * 4096 + sw;
;   asm volatile("" : "+v"(aB), "+v"(bB));
;   const int nt = K / BK;
;   for (int wg0 = vb; wg0 < nwg; wg0 += nvb) {
;     int wgid = wg0;
;     { int q = nwg / NXCD, r = nwg % NXCD, xcd = wgid % NXCD, off = wgid / NXCD;
;       wgid = (xcd < r ? xcd * (q + 1) : r * (q + 1) + (xcd - r) * q) + off; }
;     int nig = WGM * nN, gid = wgid / nig, fm = gid * WGM, gsz = min(nM - fm, WGM);
;     int pm = fm + ((wgid % nig) % gsz), pn = (wgid % nig) / gsz, brow = pm * BM, bcol = pn * BM;
.LBB0_148:
	v_lshlrev_b32_e32 v1, 6, v164
	v_lshlrev_b32_e32 v146, 2, v164
	v_lshrrev_b32_e32 v150, 8, v164
	v_and_b32_e32 v0, 48, v164
	v_and_b32_e32 v2, 0x3c0, v1
	v_and_b32_e32 v4, 32, v146
	v_or_b32_e32 v3, v2, v0
	v_bitop3_b32 v0, v2, v4, v0 bitop3:0x36
	v_lshlrev_b32_e32 v2, 13, v150
	v_and_b32_e32 v1, 0x3000, v1
	s_mov_b32 s3, 0x10000
	v_bitop3_b32 v147, v3, v2, v4 bitop3:0xde
	v_or3_b32 v148, v1, v0, s3
	v_mov_b32_e32 v149, v148
	v_mov_b32_e32 v151, v147
	s_cmpk_gt_i32 s2, 0x67f
	v_cmp_eq_u32_e64 s[4:5], 1, v150
	s_cbranch_scc1 .LBB0_166
	s_add_u32 s3, s56, 0x4000000
	s_addc_u32 s15, s57, 0
	v_lshlrev_b32_e32 v152, 4, v164
	v_and_b32_e32 v0, 32, v164
	s_add_u32 s33, s56, 0x1de00000
	v_bitop3_b32 v0, v152, v0, 48 bitop3:0x6c
	s_addc_u32 s34, s57, 0
	v_and_or_b32 v1, v164, 64, v0
	v_lshrrev_b32_e32 v2, 3, v164
	v_bfe_u32 v3, v164, 2, 4
	s_movk_i32 s6, 0x70
	s_add_u32 s10, s56, 0x2b000000
	v_lshrrev_b32_e32 v0, 1, v1
	v_and_or_b32 v2, v2, s6, v3
	v_lshlrev_b32_e32 v4, 9, v164
	s_addc_u32 s11, s57, 0
	v_lshl_or_b32 v0, v2, 12, v0
	v_lshrrev_b16_e32 v1, 1, v1
	v_and_b32_e32 v4, 0xffff0000, v4
	v_lshlrev_b32_e32 v3, 12, v3
	s_add_u32 s12, s56, 0x2b200000
	v_add_u32_e32 v2, 0x40000, v0
	v_mov_b32_e32 v129, 0
	s_movk_i32 s6, 0x100
	v_or3_b32 v128, v1, v4, v3
	v_mov_b32_e32 v1, 0x80000
	s_addc_u32 s13, s57, 0
	v_cmp_gt_u32_e64 s[6:7], s6, v164
	v_lshlrev_b64 v[130:131], 1, v[128:129]
	v_lshl_add_u32 v132, v128, 1, v1
	v_mov_b32_e32 v133, v129
	s_movk_i32 s35, 0xd1
	v_lshlrev_b32_e32 v134, 1, v0
	v_mov_b32_e32 v135, v129
	v_add_u32_e32 v153, 0x10000, v152
	v_lshlrev_b32_e32 v136, 1, v2
	v_mov_b32_e32 v137, v129
	v_add_u32_e32 v154, 0x12000, v152
	v_add_u32_e32 v155, 0x2000, v152
	v_add_u32_e32 v156, 0x14000, v152
	v_add_u32_e32 v157, 0x16000, v152
	v_add_u32_e32 v158, 0x4000, v152
	v_add_u32_e32 v159, 0x6000, v152
	s_mov_b64 s[38:39], 0x80
	v_add_u32_e32 v160, 0x18000, v152
	v_add_u32_e32 v161, 0x1a000, v152
	v_add_u32_e32 v162, 0x8000, v152
	v_add_u32_e32 v163, 0xa000, v152
	v_add_u32_e32 v165, 0x1c000, v152
	v_add_u32_e32 v166, 0x1e000, v152
	s_mov_b64 s[40:41], 0x100080
	v_add_u32_e32 v167, 0xc000, v152
	v_add_u32_e32 v168, 0xe000, v152
	s_mov_b64 s[42:43], 0x4000100
	s_mov_b64 s[44:45], 0x4100100
	s_mov_b64 s[48:49], 0x100
	s_mov_b64 s[50:51], 0x100100
	s_mov_b64 s[60:61], 0x4000180
	s_mov_b64 s[62:63], 0x4100180
	s_mov_b64 s[64:65], 0x180
	s_movk_i32 s81, 0x6800
	v_mov_b32_e32 v169, 0x3db504f3
	s_mov_b32 s82, s2
	s_cmp_eq_u32 s14, 0x100
	s_cbranch_scc0 .LBB0_151
	s_cmpk_ge_i32 s2, 0xf0
	s_cbranch_scc1 .LBB0_166
	s_branch .LBB0_151
.LBB0_150:
	s_waitcnt lgkmcnt(0)
	s_barrier
	s_cmp_eq_u32 s14, 0x100
	s_cbranch_scc0 .Lp1_generic_stride
	s_addk_i32 s82, 0xf0
	s_branch .Lp1_stride_done
.Lp1_generic_stride:
	s_add_i32 s82, s82, s14
.Lp1_stride_done:
	s_cmpk_lt_i32 s82, 0x680
	s_cbranch_scc0 .LBB0_166
